# gu ctx ring: last two MFMAs of each k-stage deferred past the next barrier to cover DMA issue and ds_read latency (MFMA/LDS interleave)
# speedup vs baseline: 1.0073x; 1.0073x over previous
; #define MFMA(a, b, c) __builtin_amdgcn_mfma_f32_32x32x16_bf16((a), (b), (c), 0, 0, 0)
; #define TIDX opaque_tid()
; template <int AI, int BI>
; DI void gemm_stage(const u16* __restrict__ A, int lda, const u16* __restrict__ B, int ldb, char* buf, int tid) {
; #pragma unroll
;   for (int i = 0; i < 2 * AI; ++i) {
;     const int S = tid + NTHR * i, row = S >> 3, c = (S & 7) ^ ((row >> 1) & 7);
;     __builtin_amdgcn_global_load_lds((const unsigned*)(A + (size_t)row * lda + c * 8), (__attribute__((address_space(3))) unsigned*)(buf + S * 16), 16, 0, 0);
;   }
; #pragma unroll
;   for (int i = 0; i < 2 * BI; ++i) {
;     const int S = tid + NTHR * i, row = S >> 3, c = (S & 7) ^ ((row >> 1) & 7);
;     __builtin_amdgcn_global_load_lds((const unsigned*)(B + (size_t)row * ldb + c * 8), (__attribute__((address_space(3))) unsigned*)(buf + 16384 + S * 16), 16, 0, 0);
;   }
; }
; template <int AI, int BI>
; DI void gemm_tile(const u16* __restrict__ A, int lda, const u16* __restrict__ B, int ldb, int nk, bool swap,
;                   f32x16 (&acc)[AI][BI], char* lds) {
;   const int tid = TIDX, lane = tid & 63, wid = tid >> 6;
;   gemm_stage<AI, BI>(A, lda, B, ldb, lds, tid);
;   asm volatile("s_waitcnt vmcnt(0)" ::: "memory");
;   __syncthreads();
;   const int wa = wid >> 1, wb = wid & 1, r = lane & 31, h = lane >> 5, sw = (r >> 1) & 7;
;   const int offA = (swap ? 16384 : 0) + (wa * 32 * AI + r) * 128;
;   const int offB = (swap ? 0 : 16384) + (wb * 32 * BI + r) * 128;
;   for (int kt = 0; kt < nk; ++kt) {
;     const char* cur = lds + (kt & 1) * 32768;
;     if (kt + 1 < nk) gemm_stage<AI, BI>(A + (kt + 1) * 64, lda, B + (kt + 1) * 64, ldb, lds + ((kt + 1) & 1) * 32768, tid);
; #pragma unroll
;     for (int ks = 0; ks < 4; ++ks) {
;       const int co = ((ks * 2 + h) ^ sw) << 4;
;       s16x8 fa[AI], fb[BI];
; #pragma unroll
;       for (int i = 0; i < AI; ++i) fa[i] = *(const s16x8*)(cur + offA + i * 4096 + co);
; #pragma unroll
;       for (int i = 0; i < BI; ++i) fb[i] = *(const s16x8*)(cur + offB + i * 4096 + co);
; #pragma unroll
;       for (int i = 0; i < AI; ++i)
; #pragma unroll
;         for (int j = 0; j < BI; ++j) acc[i][j] = MFMA(fa[i], fb[j], acc[i][j]);
;     }
;     asm volatile("s_waitcnt vmcnt(0)" ::: "memory");
;     __syncthreads();
;   }
.Lgc1_w0_j:
	s_barrier
	s_add_u32 m0, s17, 65664
	s_nop 0
	global_load_lds_dwordx4 v90, s[8:9]
	s_add_u32 m0, s17, 69760
	s_nop 0
	global_load_lds_dwordx4 v91, s[8:9]
	s_add_u32 m0, s17, 32768
	s_nop 0
	global_load_lds_dwordx4 v90, s[28:29]
	s_add_u32 m0, s17, 36864
	s_nop 0
	global_load_lds_dwordx4 v91, s[28:29]
	s_add_u32 m0, s17, 40960
	s_nop 0
	global_load_lds_dwordx4 v92, s[28:29]
	s_add_u32 m0, s17, 45056
	s_nop 0
	global_load_lds_dwordx4 v93, s[28:29]
	s_add_u32 s8, s8, 0x80
	s_addc_u32 s9, s9, 0
	s_add_u32 s28, s28, 0x80
	s_addc_u32 s29, s29, 0
	ds_read_b128 v[34:37], v82 offset:0
	ds_read_b128 v[38:41], v86 offset:0
	ds_read_b128 v[42:45], v86 offset:4096
	ds_read_b128 v[46:49], v83 offset:0
	ds_read_b128 v[50:53], v87 offset:0
	ds_read_b128 v[54:57], v87 offset:4096
	ds_read_b128 v[58:61], v84 offset:0
	ds_read_b128 v[62:65], v88 offset:0
	ds_read_b128 v[66:69], v88 offset:4096
	ds_read_b128 v[70:73], v85 offset:0
	ds_read_b128 v[74:77], v89 offset:0
	ds_read_b128 v[78:81], v89 offset:4096
	s_waitcnt lgkmcnt(10)
	v_mfma_f32_32x32x16_bf16 v[2:17], v[34:37], v[38:41], v[2:17]
	s_waitcnt lgkmcnt(9)
	v_mfma_f32_32x32x16_bf16 v[18:33], v[34:37], v[42:45], v[18:33]
	s_waitcnt lgkmcnt(7)
	v_mfma_f32_32x32x16_bf16 v[2:17], v[46:49], v[50:53], v[2:17]
	s_waitcnt lgkmcnt(6)
	v_mfma_f32_32x32x16_bf16 v[18:33], v[46:49], v[54:57], v[18:33]
	s_waitcnt lgkmcnt(4)
	v_mfma_f32_32x32x16_bf16 v[2:17], v[58:61], v[62:65], v[2:17]
	s_waitcnt lgkmcnt(3)
	v_mfma_f32_32x32x16_bf16 v[18:33], v[58:61], v[66:69], v[18:33]
	s_cmp_eq_u32 s32, 0
	s_cbranch_scc1 .Lgc1_w1_f
	s_waitcnt vmcnt(22)
	s_branch .Lgc1_w1_j

; #define MFMA(a, b, c) __builtin_amdgcn_mfma_f32_32x32x16_bf16((a), (b), (c), 0, 0, 0)
; #define TIDX opaque_tid()
; template <int AI, int BI>
; DI void gemm_stage(const u16* __restrict__ A, int lda, const u16* __restrict__ B, int ldb, char* buf, int tid) {
; #pragma unroll
;   for (int i = 0; i < 2 * AI; ++i) {
;     const int S = tid + NTHR * i, row = S >> 3, c = (S & 7) ^ ((row >> 1) & 7);
;     __builtin_amdgcn_global_load_lds((const unsigned*)(A + (size_t)row * lda + c * 8), (__attribute__((address_space(3))) unsigned*)(buf + S * 16), 16, 0, 0);
;   }
; #pragma unroll
;   for (int i = 0; i < 2 * BI; ++i) {
;     const int S = tid + NTHR * i, row = S >> 3, c = (S & 7) ^ ((row >> 1) & 7);
;     __builtin_amdgcn_global_load_lds((const unsigned*)(B + (size_t)row * ldb + c * 8), (__attribute__((address_space(3))) unsigned*)(buf + 16384 + S * 16), 16, 0, 0);
;   }
; }
; template <int AI, int BI>
; DI void gemm_tile(const u16* __restrict__ A, int lda, const u16* __restrict__ B, int ldb, int nk, bool swap,
;                   f32x16 (&acc)[AI][BI], char* lds) {
;   const int tid = TIDX, lane = tid & 63, wid = tid >> 6;
;   gemm_stage<AI, BI>(A, lda, B, ldb, lds, tid);
;   asm volatile("s_waitcnt vmcnt(0)" ::: "memory");
;   __syncthreads();
;   const int wa = wid >> 1, wb = wid & 1, r = lane & 31, h = lane >> 5, sw = (r >> 1) & 7;
;   const int offA = (swap ? 16384 : 0) + (wa * 32 * AI + r) * 128;
;   const int offB = (swap ? 0 : 16384) + (wb * 32 * BI + r) * 128;
;   for (int kt = 0; kt < nk; ++kt) {
;     const char* cur = lds + (kt & 1) * 32768;
;     if (kt + 1 < nk) gemm_stage<AI, BI>(A + (kt + 1) * 64, lda, B + (kt + 1) * 64, ldb, lds + ((kt + 1) & 1) * 32768, tid);
; #pragma unroll
;     for (int ks = 0; ks < 4; ++ks) {
;       const int co = ((ks * 2 + h) ^ sw) << 4;
;       s16x8 fa[AI], fb[BI];
; #pragma unroll
;       for (int i = 0; i < AI; ++i) fa[i] = *(const s16x8*)(cur + offA + i * 4096 + co);
; #pragma unroll
;       for (int i = 0; i < BI; ++i) fb[i] = *(const s16x8*)(cur + offB + i * 4096 + co);
; #pragma unroll
;       for (int i = 0; i < AI; ++i)
; #pragma unroll
;         for (int j = 0; j < BI; ++j) acc[i][j] = MFMA(fa[i], fb[j], acc[i][j]);
;     }
;     asm volatile("s_waitcnt vmcnt(0)" ::: "memory");
;     __syncthreads();
;   }
.Lgc1_w1_j:
	s_barrier
	s_add_u32 m0, s17, 49152
	s_nop 0
	global_load_lds_dwordx4 v90, s[8:9]
	s_add_u32 m0, s17, 53248
	s_nop 0
	global_load_lds_dwordx4 v91, s[8:9]
	s_add_u32 m0, s17, 0
	s_nop 0
	global_load_lds_dwordx4 v90, s[28:29]
	s_add_u32 m0, s17, 4096
	s_nop 0
	global_load_lds_dwordx4 v91, s[28:29]
	s_add_u32 m0, s17, 8192
	s_nop 0
	global_load_lds_dwordx4 v92, s[28:29]
	s_add_u32 m0, s17, 12288
	s_nop 0
	global_load_lds_dwordx4 v93, s[28:29]
	s_add_u32 s8, s8, 0x80
	s_addc_u32 s9, s9, 0
	s_add_u32 s28, s28, 0x80
	s_addc_u32 s29, s29, 0
	ds_read_b128 v[34:37], v82 offset:8192
	ds_read_b128 v[38:41], v86 offset:16384
	ds_read_b128 v[42:45], v86 offset:20480
	ds_read_b128 v[46:49], v83 offset:8192
	ds_read_b128 v[50:53], v87 offset:16384
	ds_read_b128 v[54:57], v87 offset:20480
	ds_read_b128 v[58:61], v84 offset:8192
	ds_read_b128 v[62:65], v88 offset:16384
	ds_read_b128 v[66:69], v88 offset:20480
	s_waitcnt lgkmcnt(9)
	v_mfma_f32_32x32x16_bf16 v[2:17], v[70:73], v[74:77], v[2:17]
	v_mfma_f32_32x32x16_bf16 v[18:33], v[70:73], v[78:81], v[18:33]
	ds_read_b128 v[70:73], v85 offset:8192
	ds_read_b128 v[74:77], v89 offset:16384
	ds_read_b128 v[78:81], v89 offset:20480
	s_waitcnt lgkmcnt(10)
	v_mfma_f32_32x32x16_bf16 v[2:17], v[34:37], v[38:41], v[2:17]
	s_waitcnt lgkmcnt(9)
	v_mfma_f32_32x32x16_bf16 v[18:33], v[34:37], v[42:45], v[18:33]
	s_waitcnt lgkmcnt(7)
	v_mfma_f32_32x32x16_bf16 v[2:17], v[46:49], v[50:53], v[2:17]
	s_waitcnt lgkmcnt(6)
	v_mfma_f32_32x32x16_bf16 v[18:33], v[46:49], v[54:57], v[18:33]
	s_waitcnt lgkmcnt(4)
	v_mfma_f32_32x32x16_bf16 v[2:17], v[58:61], v[62:65], v[2:17]
	s_waitcnt lgkmcnt(3)
	v_mfma_f32_32x32x16_bf16 v[18:33], v[58:61], v[66:69], v[18:33]
	s_waitcnt vmcnt(6)
	s_barrier
	s_add_u32 m0, s17, 57344
	s_nop 0
	global_load_lds_dwordx4 v90, s[8:9]
	s_add_u32 m0, s17, 61440
	s_nop 0
	global_load_lds_dwordx4 v91, s[8:9]
	s_add_u32 m0, s17, 16384
	s_nop 0
	global_load_lds_dwordx4 v90, s[28:29]
	s_add_u32 m0, s17, 20480
	s_nop 0
	global_load_lds_dwordx4 v91, s[28:29]
	s_add_u32 m0, s17, 24576
	s_nop 0
	global_load_lds_dwordx4 v92, s[28:29]
	s_add_u32 m0, s17, 28672
	s_nop 0
	global_load_lds_dwordx4 v93, s[28:29]
	s_add_u32 s8, s8, 0x80
	s_addc_u32 s9, s9, 0
	s_add_u32 s28, s28, 0x80
	s_addc_u32 s29, s29, 0
	ds_read_b128 v[34:37], v82 offset:16512
	ds_read_b128 v[38:41], v86 offset:32768
	ds_read_b128 v[42:45], v86 offset:36864
	ds_read_b128 v[46:49], v83 offset:16512
	ds_read_b128 v[50:53], v87 offset:32768
	ds_read_b128 v[54:57], v87 offset:36864
	ds_read_b128 v[58:61], v84 offset:16512
	ds_read_b128 v[62:65], v88 offset:32768
	ds_read_b128 v[66:69], v88 offset:36864
	s_waitcnt lgkmcnt(9)
	v_mfma_f32_32x32x16_bf16 v[2:17], v[70:73], v[74:77], v[2:17]
	v_mfma_f32_32x32x16_bf16 v[18:33], v[70:73], v[78:81], v[18:33]
	ds_read_b128 v[70:73], v85 offset:16512
	ds_read_b128 v[74:77], v89 offset:32768
	ds_read_b128 v[78:81], v89 offset:36864
	s_waitcnt lgkmcnt(10)
	v_mfma_f32_32x32x16_bf16 v[2:17], v[34:37], v[38:41], v[2:17]
	s_waitcnt lgkmcnt(9)
	v_mfma_f32_32x32x16_bf16 v[18:33], v[34:37], v[42:45], v[18:33]
	s_waitcnt lgkmcnt(7)
	v_mfma_f32_32x32x16_bf16 v[2:17], v[46:49], v[50:53], v[2:17]
	s_waitcnt lgkmcnt(6)
	v_mfma_f32_32x32x16_bf16 v[18:33], v[46:49], v[54:57], v[18:33]
	s_waitcnt lgkmcnt(4)
	v_mfma_f32_32x32x16_bf16 v[2:17], v[58:61], v[62:65], v[2:17]
	s_waitcnt lgkmcnt(3)
	v_mfma_f32_32x32x16_bf16 v[18:33], v[58:61], v[66:69], v[18:33]
	s_mov_b32 s18, 3
.Lgc1_kloop:
	s_waitcnt vmcnt(6)
	s_barrier
	s_add_u32 m0, s17, 65664
	s_nop 0
	global_load_lds_dwordx4 v90, s[8:9]
	s_add_u32 m0, s17, 69760
	s_nop 0
	global_load_lds_dwordx4 v91, s[8:9]
	s_add_u32 m0, s17, 32768
	s_nop 0
	global_load_lds_dwordx4 v90, s[28:29]
	s_add_u32 m0, s17, 36864
	s_nop 0
	global_load_lds_dwordx4 v91, s[28:29]
	s_add_u32 m0, s17, 40960
	s_nop 0
	global_load_lds_dwordx4 v92, s[28:29]
	s_add_u32 m0, s17, 45056
	s_nop 0
	global_load_lds_dwordx4 v93, s[28:29]
	s_add_u32 s8, s8, 0x80
	s_addc_u32 s9, s9, 0
	s_add_u32 s28, s28, 0x80
	s_addc_u32 s29, s29, 0
	ds_read_b128 v[34:37], v82 offset:0
	ds_read_b128 v[38:41], v86 offset:0
	ds_read_b128 v[42:45], v86 offset:4096
	ds_read_b128 v[46:49], v83 offset:0
	ds_read_b128 v[50:53], v87 offset:0
	ds_read_b128 v[54:57], v87 offset:4096
	ds_read_b128 v[58:61], v84 offset:0
	ds_read_b128 v[62:65], v88 offset:0
	ds_read_b128 v[66:69], v88 offset:4096
	s_waitcnt lgkmcnt(9)
	v_mfma_f32_32x32x16_bf16 v[2:17], v[70:73], v[74:77], v[2:17]
	v_mfma_f32_32x32x16_bf16 v[18:33], v[70:73], v[78:81], v[18:33]
	ds_read_b128 v[70:73], v85 offset:0
	ds_read_b128 v[74:77], v89 offset:0
	ds_read_b128 v[78:81], v89 offset:4096
	s_waitcnt lgkmcnt(10)
	v_mfma_f32_32x32x16_bf16 v[2:17], v[34:37], v[38:41], v[2:17]
	s_waitcnt lgkmcnt(9)
	v_mfma_f32_32x32x16_bf16 v[18:33], v[34:37], v[42:45], v[18:33]
	s_waitcnt lgkmcnt(7)
	v_mfma_f32_32x32x16_bf16 v[2:17], v[46:49], v[50:53], v[2:17]
	s_waitcnt lgkmcnt(6)
	v_mfma_f32_32x32x16_bf16 v[18:33], v[46:49], v[54:57], v[18:33]
	s_waitcnt lgkmcnt(4)
	v_mfma_f32_32x32x16_bf16 v[2:17], v[58:61], v[62:65], v[2:17]
	s_waitcnt lgkmcnt(3)
	v_mfma_f32_32x32x16_bf16 v[18:33], v[58:61], v[66:69], v[18:33]
	s_waitcnt vmcnt(6)
	s_barrier
; #define MFMA(a, b, c) __builtin_amdgcn_mfma_f32_32x32x16_bf16((a), (b), (c), 0, 0, 0)
; #define TIDX opaque_tid()
; template <int AI, int BI>
; DI void gemm_stage(const u16* __restrict__ A, int lda, const u16* __restrict__ B, int ldb, char* buf, int tid) {
; #pragma unroll
;   for (int i = 0; i < 2 * AI; ++i) {
;     const int S = tid + NTHR * i, row = S >> 3, c = (S & 7) ^ ((row >> 1) & 7);
;     __builtin_amdgcn_global_load_lds((const unsigned*)(A + (size_t)row * lda + c * 8), (__attribute__((address_space(3))) unsigned*)(buf + S * 16), 16, 0, 0);
;   }
; #pragma unroll
;   for (int i = 0; i < 2 * BI; ++i) {
;     const int S = tid + NTHR * i, row = S >> 3, c = (S & 7) ^ ((row >> 1) & 7);
;     __builtin_amdgcn_global_load_lds((const unsigned*)(B + (size_t)row * ldb + c * 8), (__attribute__((address_space(3))) unsigned*)(buf + 16384 + S * 16), 16, 0, 0);
;   }
; }
; template <int AI, int BI>
; DI void gemm_tile(const u16* __restrict__ A, int lda, const u16* __restrict__ B, int ldb, int nk, bool swap,
;                   f32x16 (&acc)[AI][BI], char* lds) {
;   const int tid = TIDX, lane = tid & 63, wid = tid >> 6;
;   gemm_stage<AI, BI>(A, lda, B, ldb, lds, tid);
;   asm volatile("s_waitcnt vmcnt(0)" ::: "memory");
;   __syncthreads();
;   const int wa = wid >> 1, wb = wid & 1, r = lane & 31, h = lane >> 5, sw = (r >> 1) & 7;
;   const int offA = (swap ? 16384 : 0) + (wa * 32 * AI + r) * 128;
;   const int offB = (swap ? 0 : 16384) + (wb * 32 * BI + r) * 128;
;   for (int kt = 0; kt < nk; ++kt) {
;     const char* cur = lds + (kt & 1) * 32768;
;     if (kt + 1 < nk) gemm_stage<AI, BI>(A + (kt + 1) * 64, lda, B + (kt + 1) * 64, ldb, lds + ((kt + 1) & 1) * 32768, tid);
; #pragma unroll
;     for (int ks = 0; ks < 4; ++ks) {
;       const int co = ((ks * 2 + h) ^ sw) << 4;
;       s16x8 fa[AI], fb[BI];
; #pragma unroll
;       for (int i = 0; i < AI; ++i) fa[i] = *(const s16x8*)(cur + offA + i * 4096 + co);
; #pragma unroll
;       for (int i = 0; i < BI; ++i) fb[i] = *(const s16x8*)(cur + offB + i * 4096 + co);
; #pragma unroll
;       for (int i = 0; i < AI; ++i)
; #pragma unroll
;         for (int j = 0; j < BI; ++j) acc[i][j] = MFMA(fa[i], fb[j], acc[i][j]);
;     }
;     asm volatile("s_waitcnt vmcnt(0)" ::: "memory");
;     __syncthreads();
;   }
	s_add_u32 m0, s17, 49152
	s_nop 0
	global_load_lds_dwordx4 v90, s[8:9]
	s_add_u32 m0, s17, 53248
	s_nop 0
	global_load_lds_dwordx4 v91, s[8:9]
	s_add_u32 m0, s17, 0
	s_nop 0
	global_load_lds_dwordx4 v90, s[28:29]
	s_add_u32 m0, s17, 4096
	s_nop 0
	global_load_lds_dwordx4 v91, s[28:29]
	s_add_u32 m0, s17, 8192
	s_nop 0
	global_load_lds_dwordx4 v92, s[28:29]
	s_add_u32 m0, s17, 12288
	s_nop 0
	global_load_lds_dwordx4 v93, s[28:29]
	s_add_u32 s8, s8, 0x80
	s_addc_u32 s9, s9, 0
	s_add_u32 s28, s28, 0x80
	s_addc_u32 s29, s29, 0
	ds_read_b128 v[34:37], v82 offset:8192
	ds_read_b128 v[38:41], v86 offset:16384
	ds_read_b128 v[42:45], v86 offset:20480
	ds_read_b128 v[46:49], v83 offset:8192
	ds_read_b128 v[50:53], v87 offset:16384
	ds_read_b128 v[54:57], v87 offset:20480
	ds_read_b128 v[58:61], v84 offset:8192
	ds_read_b128 v[62:65], v88 offset:16384
	ds_read_b128 v[66:69], v88 offset:20480
	s_waitcnt lgkmcnt(9)
	v_mfma_f32_32x32x16_bf16 v[2:17], v[70:73], v[74:77], v[2:17]
	v_mfma_f32_32x32x16_bf16 v[18:33], v[70:73], v[78:81], v[18:33]
	ds_read_b128 v[70:73], v85 offset:8192
	ds_read_b128 v[74:77], v89 offset:16384
	ds_read_b128 v[78:81], v89 offset:20480
	s_waitcnt lgkmcnt(10)
	v_mfma_f32_32x32x16_bf16 v[2:17], v[34:37], v[38:41], v[2:17]
	s_waitcnt lgkmcnt(9)
	v_mfma_f32_32x32x16_bf16 v[18:33], v[34:37], v[42:45], v[18:33]
	s_waitcnt lgkmcnt(7)
	v_mfma_f32_32x32x16_bf16 v[2:17], v[46:49], v[50:53], v[2:17]
	s_waitcnt lgkmcnt(6)
	v_mfma_f32_32x32x16_bf16 v[18:33], v[46:49], v[54:57], v[18:33]
	s_waitcnt lgkmcnt(4)
	v_mfma_f32_32x32x16_bf16 v[2:17], v[58:61], v[62:65], v[2:17]
	s_waitcnt lgkmcnt(3)
	v_mfma_f32_32x32x16_bf16 v[18:33], v[58:61], v[66:69], v[18:33]
	s_waitcnt vmcnt(6)
	s_barrier
	s_add_u32 m0, s17, 57344
	s_nop 0
	global_load_lds_dwordx4 v90, s[8:9]
	s_add_u32 m0, s17, 61440
	s_nop 0
	global_load_lds_dwordx4 v91, s[8:9]
	s_add_u32 m0, s17, 16384
	s_nop 0
	global_load_lds_dwordx4 v90, s[28:29]
	s_add_u32 m0, s17, 20480
	s_nop 0
	global_load_lds_dwordx4 v91, s[28:29]
	s_add_u32 m0, s17, 24576
	s_nop 0
	global_load_lds_dwordx4 v92, s[28:29]
	s_add_u32 m0, s17, 28672
	s_nop 0
	global_load_lds_dwordx4 v93, s[28:29]
	s_add_u32 s8, s8, 0x80
	s_addc_u32 s9, s9, 0
	s_add_u32 s28, s28, 0x80
	s_addc_u32 s29, s29, 0
	ds_read_b128 v[34:37], v82 offset:16512
	ds_read_b128 v[38:41], v86 offset:32768
	ds_read_b128 v[42:45], v86 offset:36864
	ds_read_b128 v[46:49], v83 offset:16512
	ds_read_b128 v[50:53], v87 offset:32768
	ds_read_b128 v[54:57], v87 offset:36864
	ds_read_b128 v[58:61], v84 offset:16512
	ds_read_b128 v[62:65], v88 offset:32768
	ds_read_b128 v[66:69], v88 offset:36864
	s_waitcnt lgkmcnt(9)
	v_mfma_f32_32x32x16_bf16 v[2:17], v[70:73], v[74:77], v[2:17]
	v_mfma_f32_32x32x16_bf16 v[18:33], v[70:73], v[78:81], v[18:33]
	ds_read_b128 v[70:73], v85 offset:16512
	ds_read_b128 v[74:77], v89 offset:32768
	ds_read_b128 v[78:81], v89 offset:36864
	s_waitcnt lgkmcnt(10)
	v_mfma_f32_32x32x16_bf16 v[2:17], v[34:37], v[38:41], v[2:17]
	s_waitcnt lgkmcnt(9)
	v_mfma_f32_32x32x16_bf16 v[18:33], v[34:37], v[42:45], v[18:33]
	s_waitcnt lgkmcnt(7)
	v_mfma_f32_32x32x16_bf16 v[2:17], v[46:49], v[50:53], v[2:17]
	s_waitcnt lgkmcnt(6)
	v_mfma_f32_32x32x16_bf16 v[18:33], v[46:49], v[54:57], v[18:33]
	s_waitcnt lgkmcnt(4)
	v_mfma_f32_32x32x16_bf16 v[2:17], v[58:61], v[62:65], v[2:17]
	s_waitcnt lgkmcnt(3)
	v_mfma_f32_32x32x16_bf16 v[18:33], v[58:61], v[66:69], v[18:33]
	s_sub_u32 s18, s18, 1
	s_cmp_lg_u32 s18, 0
	s_cbranch_scc1 .Lgc1_kloop
	s_waitcnt vmcnt(6)
	s_barrier
	s_add_u32 m0, s17, 65664
	s_nop 0
	global_load_lds_dwordx4 v90, s[8:9]
	s_add_u32 m0, s17, 69760
	s_nop 0
	global_load_lds_dwordx4 v91, s[8:9]
	s_add_u32 m0, s17, 32768
	s_nop 0
	global_load_lds_dwordx4 v90, s[28:29]
	s_add_u32 m0, s17, 36864
	s_nop 0
	global_load_lds_dwordx4 v91, s[28:29]
	s_add_u32 m0, s17, 40960
	s_nop 0
	global_load_lds_dwordx4 v92, s[28:29]
	s_add_u32 m0, s17, 45056
	s_nop 0
	global_load_lds_dwordx4 v93, s[28:29]
	s_add_u32 s8, s8, 0x80
	s_addc_u32 s9, s9, 0
	s_add_u32 s28, s28, 0x80
	s_addc_u32 s29, s29, 0
	ds_read_b128 v[34:37], v82 offset:0
	ds_read_b128 v[38:41], v86 offset:0
	ds_read_b128 v[42:45], v86 offset:4096
	ds_read_b128 v[46:49], v83 offset:0
	ds_read_b128 v[50:53], v87 offset:0
	ds_read_b128 v[54:57], v87 offset:4096
	ds_read_b128 v[58:61], v84 offset:0
	ds_read_b128 v[62:65], v88 offset:0
	ds_read_b128 v[66:69], v88 offset:4096
	s_waitcnt lgkmcnt(9)
	v_mfma_f32_32x32x16_bf16 v[2:17], v[70:73], v[74:77], v[2:17]
	v_mfma_f32_32x32x16_bf16 v[18:33], v[70:73], v[78:81], v[18:33]
	ds_read_b128 v[70:73], v85 offset:0
	ds_read_b128 v[74:77], v89 offset:0
	ds_read_b128 v[78:81], v89 offset:4096
	s_waitcnt lgkmcnt(10)
	v_mfma_f32_32x32x16_bf16 v[2:17], v[34:37], v[38:41], v[2:17]
	s_waitcnt lgkmcnt(9)
	v_mfma_f32_32x32x16_bf16 v[18:33], v[34:37], v[42:45], v[18:33]
	s_waitcnt lgkmcnt(7)
	v_mfma_f32_32x32x16_bf16 v[2:17], v[46:49], v[50:53], v[2:17]
	s_waitcnt lgkmcnt(6)
	v_mfma_f32_32x32x16_bf16 v[18:33], v[46:49], v[54:57], v[18:33]
	s_waitcnt lgkmcnt(4)
	v_mfma_f32_32x32x16_bf16 v[2:17], v[58:61], v[62:65], v[2:17]
	s_waitcnt lgkmcnt(3)
	v_mfma_f32_32x32x16_bf16 v[18:33], v[58:61], v[66:69], v[18:33]
	s_waitcnt vmcnt(6)
	s_barrier
; #define MFMA(a, b, c) __builtin_amdgcn_mfma_f32_32x32x16_bf16((a), (b), (c), 0, 0, 0)
; template <int AI, int BI>
; DI void gemm_tile(const u16* __restrict__ A, int lda, const u16* __restrict__ B, int ldb, int nk, bool swap,
;                   f32x16 (&acc)[AI][BI], char* lds) {
;     ...
;   for (int kt = 0; kt < nk; ++kt) {
;     const char* cur = lds + (kt & 1) * 32768;
;     if (kt + 1 < nk) gemm_stage<AI, BI>(A + (kt + 1) * 64, lda, B + (kt + 1) * 64, ldb, lds + ((kt + 1) & 1) * 32768, tid);
; #pragma unroll
;     for (int ks = 0; ks < 4; ++ks) {
;       const int co = ((ks * 2 + h) ^ sw) << 4;
;       s16x8 fa[AI], fb[BI];
; #pragma unroll
;       for (int i = 0; i < AI; ++i) fa[i] = *(const s16x8*)(cur + offA + i * 4096 + co);
; #pragma unroll
;       for (int i = 0; i < BI; ++i) fb[i] = *(const s16x8*)(cur + offB + i * 4096 + co);
; #pragma unroll
;       for (int i = 0; i < AI; ++i)
; #pragma unroll
;         for (int j = 0; j < BI; ++j) acc[i][j] = MFMA(fa[i], fb[j], acc[i][j]);
;     }
;     asm volatile("s_waitcnt vmcnt(0)" ::: "memory");
;     __syncthreads();
;   }
; DI bool next_tile(int rnd, int MT, int NT, int& mt, int& nt) {
;   const int G8 = gridDim.x >> 3, x = blockIdx.x & 7, slot = blockIdx.x >> 3;
;   const int T = (rnd * 8 + x) * G8 + slot;
;   if (T >= MT * NT) return false;
;   const int band = T / (NT * 8), rem = T - band * NT * 8;
;   nt = rem >> 3; mt = band * 8 + (rem & 7);
;   return true;
; }
	s_add_u32 m0, s17, 49152
	s_nop 0
	global_load_lds_dwordx4 v90, s[8:9]
	s_add_u32 m0, s17, 53248
	s_nop 0
	global_load_lds_dwordx4 v91, s[8:9]
	s_add_u32 m0, s17, 0
	s_nop 0
	global_load_lds_dwordx4 v90, s[28:29]
	s_add_u32 m0, s17, 4096
	s_nop 0
	global_load_lds_dwordx4 v91, s[28:29]
	s_add_u32 m0, s17, 8192
	s_nop 0
	global_load_lds_dwordx4 v92, s[28:29]
	s_add_u32 m0, s17, 12288
	s_nop 0
	global_load_lds_dwordx4 v93, s[28:29]
	s_add_u32 s8, s8, 0x80
	s_addc_u32 s9, s9, 0
	s_add_u32 s28, s28, 0x80
	s_addc_u32 s29, s29, 0
	ds_read_b128 v[34:37], v82 offset:8192
	ds_read_b128 v[38:41], v86 offset:16384
	ds_read_b128 v[42:45], v86 offset:20480
	ds_read_b128 v[46:49], v83 offset:8192
	ds_read_b128 v[50:53], v87 offset:16384
	ds_read_b128 v[54:57], v87 offset:20480
	ds_read_b128 v[58:61], v84 offset:8192
	ds_read_b128 v[62:65], v88 offset:16384
	ds_read_b128 v[66:69], v88 offset:20480
	s_waitcnt lgkmcnt(9)
	v_mfma_f32_32x32x16_bf16 v[2:17], v[70:73], v[74:77], v[2:17]
	v_mfma_f32_32x32x16_bf16 v[18:33], v[70:73], v[78:81], v[18:33]
	ds_read_b128 v[70:73], v85 offset:8192
	ds_read_b128 v[74:77], v89 offset:16384
	ds_read_b128 v[78:81], v89 offset:20480
	s_waitcnt lgkmcnt(10)
	v_mfma_f32_32x32x16_bf16 v[2:17], v[34:37], v[38:41], v[2:17]
	s_waitcnt lgkmcnt(9)
	v_mfma_f32_32x32x16_bf16 v[18:33], v[34:37], v[42:45], v[18:33]
	s_waitcnt lgkmcnt(7)
	v_mfma_f32_32x32x16_bf16 v[2:17], v[46:49], v[50:53], v[2:17]
	s_waitcnt lgkmcnt(6)
	v_mfma_f32_32x32x16_bf16 v[18:33], v[46:49], v[54:57], v[18:33]
	s_waitcnt lgkmcnt(4)
	v_mfma_f32_32x32x16_bf16 v[2:17], v[58:61], v[62:65], v[2:17]
	s_waitcnt lgkmcnt(3)
	v_mfma_f32_32x32x16_bf16 v[18:33], v[58:61], v[66:69], v[18:33]
	s_waitcnt vmcnt(6)
	s_barrier
	ds_read_b128 v[34:37], v82 offset:16512
	ds_read_b128 v[38:41], v86 offset:32768
	ds_read_b128 v[42:45], v86 offset:36864
	ds_read_b128 v[46:49], v83 offset:16512
	ds_read_b128 v[50:53], v87 offset:32768
	ds_read_b128 v[54:57], v87 offset:36864
	ds_read_b128 v[58:61], v84 offset:16512
	ds_read_b128 v[62:65], v88 offset:32768
	ds_read_b128 v[66:69], v88 offset:36864
	s_waitcnt lgkmcnt(9)
	v_mfma_f32_32x32x16_bf16 v[2:17], v[70:73], v[74:77], v[2:17]
	v_mfma_f32_32x32x16_bf16 v[18:33], v[70:73], v[78:81], v[18:33]
	ds_read_b128 v[70:73], v85 offset:16512
	ds_read_b128 v[74:77], v89 offset:32768
	ds_read_b128 v[78:81], v89 offset:36864
	s_waitcnt lgkmcnt(10)
	v_mfma_f32_32x32x16_bf16 v[2:17], v[34:37], v[38:41], v[2:17]
	s_waitcnt lgkmcnt(9)
	v_mfma_f32_32x32x16_bf16 v[18:33], v[34:37], v[42:45], v[18:33]
	s_waitcnt lgkmcnt(7)
	v_mfma_f32_32x32x16_bf16 v[2:17], v[46:49], v[50:53], v[2:17]
	s_waitcnt lgkmcnt(6)
	v_mfma_f32_32x32x16_bf16 v[18:33], v[46:49], v[54:57], v[18:33]
	s_waitcnt lgkmcnt(4)
	v_mfma_f32_32x32x16_bf16 v[2:17], v[58:61], v[62:65], v[2:17]
	s_waitcnt lgkmcnt(3)
	v_mfma_f32_32x32x16_bf16 v[18:33], v[58:61], v[66:69], v[18:33]
	s_waitcnt vmcnt(0)
	s_barrier
	ds_read_b128 v[34:37], v82 offset:0
	ds_read_b128 v[38:41], v86 offset:0
	ds_read_b128 v[42:45], v86 offset:4096
	ds_read_b128 v[46:49], v83 offset:0
	ds_read_b128 v[50:53], v87 offset:0
	ds_read_b128 v[54:57], v87 offset:4096
	ds_read_b128 v[58:61], v84 offset:0
	ds_read_b128 v[62:65], v88 offset:0
	ds_read_b128 v[66:69], v88 offset:4096
	s_waitcnt lgkmcnt(9)
	v_mfma_f32_32x32x16_bf16 v[2:17], v[70:73], v[74:77], v[2:17]
	v_mfma_f32_32x32x16_bf16 v[18:33], v[70:73], v[78:81], v[18:33]
	ds_read_b128 v[70:73], v85 offset:0
	ds_read_b128 v[74:77], v89 offset:0
	ds_read_b128 v[78:81], v89 offset:4096
	s_waitcnt lgkmcnt(10)
	v_mfma_f32_32x32x16_bf16 v[2:17], v[34:37], v[38:41], v[2:17]
	s_waitcnt lgkmcnt(9)
	v_mfma_f32_32x32x16_bf16 v[18:33], v[34:37], v[42:45], v[18:33]
	s_waitcnt lgkmcnt(7)
	v_mfma_f32_32x32x16_bf16 v[2:17], v[46:49], v[50:53], v[2:17]
	s_waitcnt lgkmcnt(6)
	v_mfma_f32_32x32x16_bf16 v[18:33], v[46:49], v[54:57], v[18:33]
	s_waitcnt lgkmcnt(4)
	v_mfma_f32_32x32x16_bf16 v[2:17], v[58:61], v[62:65], v[2:17]
	s_waitcnt lgkmcnt(3)
	v_mfma_f32_32x32x16_bf16 v[18:33], v[58:61], v[66:69], v[18:33]
	s_waitcnt lgkmcnt(0)
	v_mfma_f32_32x32x16_bf16 v[2:17], v[70:73], v[74:77], v[2:17]
	v_mfma_f32_32x32x16_bf16 v[18:33], v[70:73], v[78:81], v[18:33]
	s_add_u32 s36, s36, 0x200
	s_cmpk_lt_u32 s36, 0x580
	s_cbranch_scc0 .Lgc1_nopf
	s_barrier
	s_mul_i32 s37, s36, 0xba2f
	s_lshr_b32 s37, s37, 24
	s_mul_i32 s40, s37, 0x160
	s_sub_u32 s40, s36, s40
	s_lshr_b32 s41, s40, 3
	s_and_b32 s40, s40, 7
	s_lshl_b32 s37, s37, 3
	s_or_b32 s37, s37, s40
	s_lshl_b32 s37, s37, 6
	s_bitset1_b32 s37, 14
	s_lshl_b32 s46, s37, 11
	s_add_u32 s8, s10, s46
	s_addc_u32 s9, s11, 0
	s_lshl_b32 s46, s41, 18
	s_add_u32 s28, s12, s46
	s_addc_u32 s29, s13, 0
	s_add_u32 m0, s17, 49152
	s_nop 0
	global_load_lds_dwordx4 v90, s[8:9]
	s_add_u32 m0, s17, 53248
	s_nop 0
	global_load_lds_dwordx4 v91, s[8:9]
	s_add_u32 m0, s17, 0
	s_nop 0
	global_load_lds_dwordx4 v90, s[28:29]
	s_add_u32 m0, s17, 4096
	s_nop 0
	global_load_lds_dwordx4 v91, s[28:29]
	s_add_u32 m0, s17, 8192
	s_nop 0
	global_load_lds_dwordx4 v92, s[28:29]
	s_add_u32 m0, s17, 12288
	s_nop 0
	global_load_lds_dwordx4 v93, s[28:29]
	s_add_u32 s8, s8, 0x80
	s_addc_u32 s9, s9, 0
	s_add_u32 s28, s28, 0x80
	s_addc_u32 s29, s29, 0
	s_add_u32 m0, s17, 57344
	s_nop 0
	global_load_lds_dwordx4 v90, s[8:9]
	s_add_u32 m0, s17, 61440
	s_nop 0
	global_load_lds_dwordx4 v91, s[8:9]
	s_add_u32 m0, s17, 16384
	s_nop 0
	global_load_lds_dwordx4 v90, s[28:29]
	s_add_u32 m0, s17, 20480
	s_nop 0
	global_load_lds_dwordx4 v91, s[28:29]
	s_add_u32 m0, s17, 24576
	s_nop 0
	global_load_lds_dwordx4 v92, s[28:29]
	s_add_u32 m0, s17, 28672
	s_nop 0
	global_load_lds_dwordx4 v93, s[28:29]
	s_add_u32 s8, s8, 0x80
	s_addc_u32 s9, s9, 0
	s_add_u32 s28, s28, 0x80
	s_addc_u32 s29, s29, 0
